# v17 + one static s_setprio 1 for waves 0-3 during the attention phase (reset at each phase start)
# speedup vs baseline: 1.0018x; 1.0018x over previous
.LBB0_12:
	s_setprio 0
	v_mov_b32_e32 v223, v206
	s_nop 0
	v_readfirstlane_b32 s14, v223
	s_ashr_i32 s0, s14, 6
	v_writelane_b32 v254, s0, 40
	s_add_i32 s71, s0, s57
	s_mul_hi_i32 s0, s12, 0x51eb851f
	s_lshr_b32 s1, s0, 31
	s_ashr_i32 s0, s0, 3
	s_add_i32 s2, s0, s1
	s_mov_b32 s0, s2
	v_writelane_b32 v254, s0, 41
	v_and_b32_e32 v222, 63, v223
	s_nop 0
	v_writelane_b32 v254, s1, 42
	s_mul_i32 s0, s2, 25
	s_sub_i32 s6, s12, s0
	v_writelane_b32 v254, s12, 43
	s_cmp_lg_u32 s6, 0
	s_mov_b64 s[0:1], -1
	s_cbranch_scc0 .LBB0_470
	s_add_i32 s0, s6, -1
	s_bfe_i32 s1, s0, 0x80000
	s_mul_i32 s1, s1, 43
	s_sext_i32_i16 s2, s1
	s_ashr_i32 s5, s2, 9
	s_bfe_u32 s1, s1, 0x1000f
	s_add_i32 s5, s5, s1
	s_mul_i32 s1, s5, 12
	s_sub_i32 s0, s0, s1
	s_bfe_i32 s2, s0, 0x80000
	s_sext_i32_i16 s0, s2
	s_cmp_gt_i32 s0, 8
	s_mov_b64 s[0:1], -1
	s_cbranch_scc0 .LBB0_15
	s_and_b32 s0, 0xffff, s2
	s_cmp_eq_u32 s0, 10
	s_cselect_b32 s1, 12, 15
	s_cmp_lg_u32 s0, 9
	s_cselect_b32 s0, s1, 11
	v_writelane_b32 v254, s0, 44
	s_mov_b64 s[0:1], 0

.LBB0_19:
	s_and_b64 s[0:1], s[0:1], exec
	v_readlane_b32 s0, v252, 13
	s_cselect_b32 s67, 0, 0x4000
	s_mul_i32 s7, s7, s0
	s_and_b64 s[0:1], exec, s[2:3]
	s_cselect_b32 s0, s4, s7
	v_writelane_b32 v254, s0, 47
	s_mov_b64 s[0:1], -1
	v_readlane_b32 s7, v254, 44
	s_cmp_lg_u32 s7, 1
	s_cbranch_scc0 .LBB0_460
	v_writelane_b32 v254, s8, 48
	s_cmp_lt_i32 s7, 5
	s_nop 0
	v_writelane_b32 v254, s9, 49
	v_writelane_b32 v254, s67, 50
	s_cbranch_scc1 .LBB0_118
	s_mov_b64 s[2:3], 0
	s_cmp_gt_i32 s7, 5
	s_mov_b64 s[8:9], 0
	s_cbranch_scc0 .LBB0_119
	s_cmp_eq_u32 s7, 6
	s_mov_b64 s[8:9], -1
	s_cbranch_scc0 .LBB0_661
	s_sext_i32_i16 s1, s5
	v_readlane_b32 s8, v254, 41
	s_lshl_b32 s0, s8, 7
	s_lshl_b32 s1, s1, 6
	v_readlane_b32 s9, v254, 42
	s_mov_b32 s22, s8
	s_add_i32 s8, s1, s0
	s_ashr_i32 s9, s8, 31
	s_lshl_b64 s[8:9], s[8:9], 2
	s_add_u32 s8, s88, s8
	s_addc_u32 s9, s89, s9
	s_and_b32 s1, s6, 0xff
	s_cmp_lt_u32 s1, 23
	s_cselect_b64 s[10:11], -1, 0
	s_and_b64 s[6:7], s[10:11], exec
	s_movk_i32 s1, 0x80
	s_cselect_b32 s5, s1, 0x180
	s_movk_i32 s1, 0x4000
	s_movk_i32 s13, 0x400
	s_cselect_b32 s1, s1, 0x6000
	s_cselect_b32 s15, s13, 0x600
	s_movk_i32 s13, 0x300
	s_cselect_b32 s6, 0x80, 0
	s_cselect_b32 s7, 0x100, 0
	s_cselect_b32 s12, 0x200, 0
	s_cselect_b32 s13, 0x100, s13
	s_cselect_b32 s36, 0x2000, 0
	s_lshr_b32 s37, s1, 6
	s_lshr_b32 s58, s1, 8
	v_readlane_b32 s18, v254, 40
	s_cmp_lt_u32 s18, 4
	s_cbranch_scc0 .Lattn_prio_done
	s_setprio 1
.Lattn_prio_done:
	s_ashr_i32 s1, s14, 8
	s_bfe_u32 s16, s14, 0x20006
	v_readlane_b32 s14, v254, 43
	s_or_b32 s57, s37, s15
	s_lshl_b32 s59, s18, 5
	s_lshl_b32 s60, s16, 5
	s_add_i32 s14, s14, 24
	s_cmp_lt_u32 s14, 49
	s_cselect_b64 vcc, -1, 0
	s_lshl_b32 s14, s1, 6
	s_lshl_b32 s16, s16, 14
	s_ashr_i32 s15, s14, 31
	s_lshl_b32 s61, s1, 7
	s_add_i32 s62, s16, 0
	s_cmp_eq_u32 s1, 1
	s_cselect_b64 s[16:17], -1, 0
	s_cmp_lt_u32 s18, 4
	s_cselect_b64 s[18:19], -1, 0
	s_ashr_i32 s1, s0, 31
	v_readlane_b32 s40, v251, 7
	s_lshl_b32 s63, s22, 6
	s_lshl_b64 s[0:1], s[0:1], 2
	v_readlane_b32 s50, v251, 17
	v_readlane_b32 s51, v251, 18
	s_add_u32 s22, s50, s0
	s_addc_u32 s23, s51, s1
	s_abs_i32 s64, s58
	v_cvt_f32_u32_e32 v0, s64
	s_sub_i32 s0, 0, s64
	v_mov_b32_e32 v2, 0x3eb60549
	v_mov_b32_e32 v3, 0x3e4ccccd
	v_rcp_iflag_f32_e32 v0, v0
	v_cndmask_b32_e32 v224, v2, v3, vcc
	v_cmp_eq_u32_e64 s[38:39], 0, v223
	v_sub_f32_e32 v225, 1.0, v224
	v_mul_f32_e32 v0, 0x4f7ffffe, v0
	v_cvt_u32_f32_e32 v0, v0
	s_ashr_i32 s65, s58, 31
	v_readlane_b32 s34, v254, 1
	v_readlane_b32 s41, v251, 8
	v_readfirstlane_b32 s1, v0
	s_mul_i32 s0, s0, s1
	s_mul_hi_u32 s0, s1, s0
	s_add_i32 s66, s1, s0
	v_readlane_b32 s42, v251, 9
	v_readlane_b32 s43, v251, 10
	v_readlane_b32 s44, v251, 11
	v_readlane_b32 s45, v251, 12
	v_readlane_b32 s46, v251, 13
	v_readlane_b32 s47, v251, 14
	v_readlane_b32 s48, v251, 15
	v_readlane_b32 s49, v251, 16
	v_readlane_b32 s52, v251, 19
	v_readlane_b32 s53, v251, 20
	v_readlane_b32 s54, v251, 21
	v_readlane_b32 s55, v251, 22
	s_branch .LBB0_26
